# sgu epilogue de-serialised: 16 u loads per half prefetched together, original loads become copies, vmcnt recomputed (15/16); placement preserved
# speedup vs baseline: 1.0173x; 1.0104x over previous
.LBB0_169:
	v_ashrrev_i32_e32 v0, 3, v143
	v_lshrrev_b32_e32 v1, 29, v0
	v_add_lshl_u32 v1, v0, v1, 3
	v_and_b32_e32 v1, 0xffffffc0, v1
	v_and_b32_e32 v2, 56, v183
	v_and_b32_e32 v0, 7, v0
	v_or3_b32 v160, v1, v2, v0
	s_mov_b32 s0, 0x2aaaaaab
	v_mul_hi_i32 v0, v160, s0
	v_lshrrev_b32_e32 v1, 31, v0
	v_ashrrev_i32_e32 v0, 5, v0
	v_ashrrev_i32_e32 v161, 31, v160
	v_add_u32_e32 v184, v0, v1
	v_lshlrev_b64 v[0:1], 8, v[160:161]
	v_or_b32_e32 v4, v0, v144
	v_mov_b32_e32 v5, v1
	v_lshlrev_b64 v[4:5], 8, v[4:5]
	v_lshl_add_u64 v[162:163], v[146:147], 0, v[4:5]
	v_or_b32_e32 v4, v0, v148
	v_mov_b32_e32 v5, v1
	v_lshlrev_b64 v[4:5], 8, v[4:5]
	v_lshlrev_b32_e32 v2, 14, v184
	v_lshl_add_u64 v[164:165], v[146:147], 0, v[4:5]
	v_or_b32_e32 v4, v0, v150
	v_or_b32_e32 v0, v0, v152
	v_ashrrev_i32_e32 v3, 31, v2
	v_mov_b32_e32 v5, v1
	v_lshlrev_b64 v[0:1], 8, v[0:1]
	v_lshl_add_u64 v[170:171], v[146:147], 0, v[0:1]
	v_lshl_add_u64 v[168:169], v[2:3], 1, v[154:155]
	v_lshlrev_b64 v[4:5], 8, v[4:5]
	v_lshl_add_u64 v[166:167], v[146:147], 0, v[4:5]
	s_movk_i32 s0, 0x4000
	v_add_co_u32_e32 v172, vcc, s0, v168
	s_movk_i32 s0, 0xc0
	s_nop 0
	v_addc_co_u32_e32 v173, vcc, 0, v169, vcc
	global_load_dwordx4 v[218:221], v[162:163], off
	global_load_dwordx4 v[222:225], v[164:165], off
	global_load_dwordx4 v[226:229], v[166:167], off
	global_load_dwordx4 v[238:241], v[170:171], off
	global_load_dwordx4 v[244:247], v[168:169], off
	global_load_dwordx4 v[248:251], v[172:173], off
	v_mul_lo_u32 v130, v184, s0
	v_sub_u32_e32 v130, v160, v130
	v_lshl_or_b32 v130, v130, 8, v145
	v_ashrrev_i32_e32 v130, 7, v130
	v_ashrrev_i32_e32 v131, 31, v130
	v_lshlrev_b64 v[130:131], 7, v[130:131]
	v_add_u32_e32 v143, s23, v143
	s_movk_i32 s0, 0x2ff
	v_cmp_lt_i32_e32 vcc, s0, v143
	v_add_u32_e32 v183, s20, v183
	s_or_b64 s[8:9], vcc, s[8:9]
	s_waitcnt vmcnt(0)
	ds_write_b128 v149, v[218:221]
	ds_write_b128 v151, v[222:225]
	ds_write_b128 v153, v[226:229]
	ds_write_b128 v157, v[238:241]
	ds_write_b128 v159, v[244:247]
	ds_write_b128 v174, v[248:251]
	s_waitcnt lgkmcnt(0)
	s_barrier
	global_load_dwordx4 v[218:221], v[162:163], off offset:64
	global_load_dwordx4 v[222:225], v[164:165], off offset:64
	global_load_dwordx4 v[226:229], v[166:167], off offset:64
	global_load_dwordx4 v[238:241], v[170:171], off offset:64
	global_load_dwordx4 v[244:247], v[168:169], off offset:64
	global_load_dwordx4 v[248:251], v[172:173], off offset:64
	ds_read_b128 v[0:3], v175 offset:2560
	ds_read_b128 v[4:7], v175 offset:5120
	ds_read_b128 v[8:11], v175 offset:7680
	ds_read_b128 v[12:15], v176 offset:23040
	ds_read_b128 v[16:19], v175
	ds_read_b128 v[186:189], v175 offset:32
	ds_read_b128 v[64:67], v176 offset:20480
	ds_read_b128 v[190:193], v176 offset:20512
	s_waitcnt lgkmcnt(1)
	v_mfma_f32_32x32x16_bf16 v[112:127], v[16:19], v[64:67], 0
	ds_read_b128 v[194:197], v175 offset:2592
	ds_read_b128 v[198:201], v175 offset:5152
	ds_read_b128 v[202:205], v175 offset:7712
	ds_read_b128 v[206:209], v176 offset:23072
	v_mfma_f32_32x32x16_bf16 v[48:63], v[16:19], v[12:15], 0
	s_waitcnt lgkmcnt(4)
	v_mfma_f32_32x32x16_bf16 v[112:127], v[186:189], v[190:193], v[112:127]
	s_waitcnt lgkmcnt(0)
	v_mfma_f32_32x32x16_bf16 v[48:63], v[186:189], v[206:209], v[48:63]
	v_mfma_f32_32x32x16_bf16 v[96:111], v[0:3], v[64:67], 0
	v_mfma_f32_32x32x16_bf16 v[32:47], v[0:3], v[12:15], 0
	v_mfma_f32_32x32x16_bf16 v[80:95], v[4:7], v[64:67], 0
	v_mfma_f32_32x32x16_bf16 v[16:31], v[4:7], v[12:15], 0
	v_mfma_f32_32x32x16_bf16 v[64:79], v[8:11], v[64:67], 0
	s_waitcnt vmcnt(0)
	ds_write_b128 v177, v[218:221]
	ds_write_b128 v178, v[222:225]
	ds_write_b128 v179, v[226:229]
	ds_write_b128 v180, v[238:241]
	ds_write_b128 v181, v[244:247]
	ds_write_b128 v182, v[248:251]
	v_mfma_f32_32x32x16_bf16 v[0:15], v[8:11], v[12:15], 0
	s_waitcnt lgkmcnt(0)
	s_barrier
	global_load_dwordx4 v[218:221], v[162:163], off offset:128
	global_load_dwordx4 v[222:225], v[164:165], off offset:128
	global_load_dwordx4 v[226:229], v[166:167], off offset:128
	global_load_dwordx4 v[238:241], v[170:171], off offset:128
	global_load_dwordx4 v[244:247], v[168:169], off offset:128
	global_load_dwordx4 v[248:251], v[172:173], off offset:128
	v_mfma_f32_32x32x16_bf16 v[96:111], v[194:197], v[190:193], v[96:111]
	v_mfma_f32_32x32x16_bf16 v[32:47], v[194:197], v[206:209], v[32:47]
	v_mfma_f32_32x32x16_bf16 v[80:95], v[198:201], v[190:193], v[80:95]
	v_mfma_f32_32x32x16_bf16 v[16:31], v[198:201], v[206:209], v[16:31]
	v_mfma_f32_32x32x16_bf16 v[64:79], v[202:205], v[190:193], v[64:79]
	v_mfma_f32_32x32x16_bf16 v[0:15], v[202:205], v[206:209], v[0:15]
	ds_read_b128 v[186:189], v175 offset:33280
	ds_read_b128 v[190:193], v175 offset:35840
	ds_read_b128 v[194:197], v175 offset:38400
	ds_read_b128 v[198:201], v176 offset:53760
	ds_read_b128 v[202:205], v175 offset:30720
	ds_read_b128 v[206:209], v175 offset:30752
	ds_read_b128 v[210:213], v176 offset:51200
	ds_read_b128 v[214:217], v176 offset:51232
	s_waitcnt lgkmcnt(1)
	v_mfma_f32_32x32x16_bf16 v[96:111], v[186:189], v[210:213], v[96:111]
	v_mfma_f32_32x32x16_bf16 v[32:47], v[186:189], v[198:201], v[32:47]
	v_mfma_f32_32x32x16_bf16 v[48:63], v[202:205], v[198:201], v[48:63]
	v_mfma_f32_32x32x16_bf16 v[80:95], v[190:193], v[210:213], v[80:95]
	v_mfma_f32_32x32x16_bf16 v[16:31], v[190:193], v[198:201], v[16:31]
	v_mfma_f32_32x32x16_bf16 v[64:79], v[194:197], v[210:213], v[64:79]
	v_mfma_f32_32x32x16_bf16 v[0:15], v[194:197], v[198:201], v[0:15]
	ds_read_b128 v[186:189], v175 offset:33312
	ds_read_b128 v[190:193], v175 offset:35872
	ds_read_b128 v[194:197], v175 offset:38432
	ds_read_b128 v[198:201], v176 offset:53792
	s_waitcnt lgkmcnt(3)
	v_mfma_f32_32x32x16_bf16 v[96:111], v[186:189], v[214:217], v[96:111]
	s_waitcnt lgkmcnt(0)
	v_mfma_f32_32x32x16_bf16 v[32:47], v[186:189], v[198:201], v[32:47]
	v_mfma_f32_32x32x16_bf16 v[112:127], v[202:205], v[210:213], v[112:127]
	v_mfma_f32_32x32x16_bf16 v[48:63], v[206:209], v[198:201], v[48:63]
	v_mfma_f32_32x32x16_bf16 v[80:95], v[190:193], v[214:217], v[80:95]
	v_mfma_f32_32x32x16_bf16 v[16:31], v[190:193], v[198:201], v[16:31]
	v_mfma_f32_32x32x16_bf16 v[64:79], v[194:197], v[214:217], v[64:79]
	s_waitcnt vmcnt(0)
	ds_write_b128 v149, v[218:221]
	ds_write_b128 v151, v[222:225]
	ds_write_b128 v153, v[226:229]
	ds_write_b128 v157, v[238:241]
	ds_write_b128 v159, v[244:247]
	ds_write_b128 v174, v[248:251]
	v_mfma_f32_32x32x16_bf16 v[0:15], v[194:197], v[198:201], v[0:15]
	s_waitcnt lgkmcnt(0)
	s_barrier
	global_load_dwordx4 v[218:221], v[162:163], off offset:192
	global_load_dwordx4 v[222:225], v[164:165], off offset:192
	global_load_dwordx4 v[226:229], v[166:167], off offset:192
	global_load_dwordx4 v[238:241], v[170:171], off offset:192
	global_load_dwordx4 v[244:247], v[168:169], off offset:192
	global_load_dwordx4 v[248:251], v[172:173], off offset:192
	v_mfma_f32_32x32x16_bf16 v[112:127], v[206:209], v[214:217], v[112:127]
	ds_read_b128 v[186:189], v175 offset:2560
	ds_read_b128 v[190:193], v175 offset:5120
	ds_read_b128 v[194:197], v175 offset:7680
	ds_read_b128 v[198:201], v176 offset:23040
	ds_read_b128 v[202:205], v175
	ds_read_b128 v[206:209], v175 offset:32
	ds_read_b128 v[210:213], v176 offset:20480
	ds_read_b128 v[214:217], v176 offset:20512
	s_waitcnt lgkmcnt(1)
	v_mfma_f32_32x32x16_bf16 v[96:111], v[186:189], v[210:213], v[96:111]
	v_mfma_f32_32x32x16_bf16 v[32:47], v[186:189], v[198:201], v[32:47]
	v_mfma_f32_32x32x16_bf16 v[48:63], v[202:205], v[198:201], v[48:63]
	v_mfma_f32_32x32x16_bf16 v[80:95], v[190:193], v[210:213], v[80:95]
	v_mfma_f32_32x32x16_bf16 v[16:31], v[190:193], v[198:201], v[16:31]
	v_mfma_f32_32x32x16_bf16 v[64:79], v[194:197], v[210:213], v[64:79]
	v_mfma_f32_32x32x16_bf16 v[0:15], v[194:197], v[198:201], v[0:15]
	ds_read_b128 v[186:189], v175 offset:2592
	ds_read_b128 v[190:193], v175 offset:5152
	ds_read_b128 v[194:197], v175 offset:7712
	ds_read_b128 v[198:201], v176 offset:23072
	s_waitcnt lgkmcnt(3)
	v_mfma_f32_32x32x16_bf16 v[96:111], v[186:189], v[214:217], v[96:111]
	s_waitcnt lgkmcnt(0)
	v_mfma_f32_32x32x16_bf16 v[32:47], v[186:189], v[198:201], v[32:47]
	v_mfma_f32_32x32x16_bf16 v[48:63], v[206:209], v[198:201], v[48:63]
	v_mfma_f32_32x32x16_bf16 v[80:95], v[190:193], v[214:217], v[80:95]
	v_mfma_f32_32x32x16_bf16 v[16:31], v[190:193], v[198:201], v[16:31]
	v_mfma_f32_32x32x16_bf16 v[64:79], v[194:197], v[214:217], v[64:79]
	v_mfma_f32_32x32x16_bf16 v[0:15], v[194:197], v[198:201], v[0:15]
	s_waitcnt vmcnt(0)
	ds_write_b128 v177, v[218:221]
	ds_write_b128 v178, v[222:225]
	ds_write_b128 v179, v[226:229]
	ds_write_b128 v180, v[238:241]
	ds_write_b128 v181, v[244:247]
	ds_write_b128 v182, v[248:251]
	v_mfma_f32_32x32x16_bf16 v[112:127], v[202:205], v[210:213], v[112:127]
	s_waitcnt lgkmcnt(0)
	s_barrier
	ds_read_b128 v[162:165], v175 offset:33280
	ds_read_b128 v[166:169], v175 offset:35840
	ds_read_b128 v[170:173], v175 offset:38400
	ds_read_b128 v[186:189], v176 offset:53760
	ds_read_b128 v[190:193], v175 offset:30720
	ds_read_b128 v[194:197], v175 offset:30752
	ds_read_b128 v[198:201], v176 offset:51200
	ds_read_b128 v[202:205], v176 offset:51232
	s_waitcnt lgkmcnt(1)
	v_mfma_f32_32x32x16_bf16 v[96:111], v[162:165], v[198:201], v[96:111]
	v_mfma_f32_32x32x16_bf16 v[32:47], v[162:165], v[186:189], v[32:47]
	v_mfma_f32_32x32x16_bf16 v[48:63], v[190:193], v[186:189], v[48:63]
	v_mfma_f32_32x32x16_bf16 v[80:95], v[166:169], v[198:201], v[80:95]
	v_mfma_f32_32x32x16_bf16 v[16:31], v[166:169], v[186:189], v[16:31]
	v_mfma_f32_32x32x16_bf16 v[64:79], v[170:173], v[198:201], v[64:79]
	v_mfma_f32_32x32x16_bf16 v[0:15], v[170:173], v[186:189], v[0:15]
	ds_read_b128 v[162:165], v175 offset:33312
	ds_read_b128 v[166:169], v175 offset:35872
	ds_read_b128 v[170:173], v175 offset:38432
	ds_read_b128 v[186:189], v176 offset:53792
	s_waitcnt lgkmcnt(0)
	s_barrier
	v_mfma_f32_32x32x16_bf16 v[96:111], v[162:165], v[202:205], v[96:111]
	v_mfma_f32_32x32x16_bf16 v[32:47], v[162:165], v[186:189], v[32:47]
	v_lshlrev_b32_e32 v162, 7, v184
	v_ashrrev_i32_e32 v163, 31, v162
	v_lshlrev_b64 v[132:133], 1, v[162:163]
	v_or_b32_e32 v164, v130, v156
	v_mov_b32_e32 v165, v131
	v_lshl_add_u64 v[134:135], s[94:95], 0, v[132:133]
	v_or_b32_e32 v136, v162, v156
	v_mfma_f32_32x32x16_bf16 v[80:95], v[166:169], v[202:205], v[80:95]
	v_ashrrev_i32_e32 v137, 31, v136
	v_lshl_add_u64 v[160:161], v[136:137], 2, s[76:77]
	global_load_dword v160, v[160:161], off
	v_lshl_add_u64 v[132:133], s[6:7], 0, v[132:133]
	v_or_b32_e32 v130, v130, v158
	v_mov_b32_e32 v137, v163
	s_waitcnt vmcnt(0)
	v_pk_add_f32 v[96:97], v[96:97], v[160:161] op_sel_hi:[1,0]
	v_mfma_f32_32x32x16_bf16 v[16:31], v[166:169], v[186:189], v[16:31]
	v_lshlrev_b64 v[166:167], 12, v[164:165]
	v_lshl_add_u64 v[166:167], v[134:135], 0, v[166:167]
	v_lshl_add_u64 v[166:167], v[166:167], 0, v[128:129]
	s_branch .Lsgu_pf0
	s_nop 0
	s_nop 0
	s_nop 0
	s_nop 0
	s_nop 0
	s_nop 0
	s_nop 0
	s_nop 0
	s_nop 0
	s_nop 0
	s_nop 0
	s_nop 0
	s_nop 0
	s_nop 0
	s_nop 0
	s_nop 0
	s_nop 0
	s_nop 0
	s_nop 0
	s_nop 0
	s_nop 0
	s_nop 0
	s_nop 0
	s_nop 0
	s_nop 0
	s_nop 0
	s_nop 0
	s_nop 0
	s_nop 0
	s_nop 0
.Lsgu_pf0d:
	v_lshlrev_b64 v[164:165], 11, v[164:165]
	v_lshl_add_u64 v[164:165], v[132:133], 0, v[164:165]
	v_pk_add_f32 v[98:99], v[98:99], v[160:161] op_sel_hi:[1,0]
	v_mfma_f32_32x32x16_bf16 v[112:127], v[206:209], v[214:217], v[112:127]
	v_add_f32_e64 v100, v100, v160
	v_add_f32_e64 v101, v101, v160
	v_add_f32_e64 v80, v80, v160
	v_add_f32_e64 v81, v81, v160
	v_add_f32_e64 v82, v82, v160
	v_add_f32_e64 v83, v83, v160
	v_pk_add_f32 v[84:85], v[84:85], v[160:161] op_sel_hi:[1,0]
	v_mfma_f32_32x32x16_bf16 v[112:127], v[190:193], v[198:201], v[112:127]
	v_mfma_f32_32x32x16_bf16 v[112:127], v[194:197], v[202:205], v[112:127]
	v_mfma_f32_32x32x16_bf16 v[64:79], v[170:173], v[202:205], v[64:79]
	s_nop 10
	v_add_f32_e64 v112, v112, v160
	v_add_f32_e64 v113, v113, v160
	v_add_f32_e64 v114, v114, v160
	v_add_f32_e64 v115, v115, v160
	v_add_f32_e64 v116, v116, v160
	v_add_f32_e64 v117, v117, v160
	v_pk_add_f32 v[118:119], v[118:119], v[160:161] op_sel_hi:[1,0]
	v_mfma_f32_32x32x16_bf16 v[0:15], v[170:173], v[186:189], v[0:15]
	v_add_f32_e64 v64, v64, v160
	v_add_f32_e64 v65, v65, v160
	v_add_f32_e64 v66, v66, v160
	v_add_f32_e64 v67, v67, v160
	v_add_f32_e64 v68, v68, v160
	v_add_f32_e64 v69, v69, v160
	s_waitcnt vmcnt(15)
	v_mov_b64_e32 v[168:169], v[162:163]
	v_lshlrev_b32_e32 v170, 16, v168
	v_and_b32_e32 v171, 0xffff0000, v168
	v_lshlrev_b32_e32 v168, 16, v169
	v_and_b32_e32 v169, 0xffff0000, v169
	v_pk_mul_f32 v[112:113], v[112:113], v[170:171]
	v_pk_mul_f32 v[114:115], v[114:115], v[168:169]
	v_cvt_pk_bf16_f32 v112, v112, v113
	v_cvt_pk_bf16_f32 v113, v114, v115
	v_lshl_add_u64 v[114:115], v[164:165], 0, v[128:129]
	global_store_dwordx2 v[114:115], v[112:113], off
	v_mfma_f32_32x32x16_bf16 v[48:63], v[194:197], v[186:189], v[48:63]
	s_waitcnt vmcnt(15)
	v_mov_b64_e32 v[112:113], v[210:211]
	v_lshlrev_b32_e32 v164, 16, v112
	v_and_b32_e32 v165, 0xffff0000, v112
	v_lshlrev_b32_e32 v112, 16, v113
	v_and_b32_e32 v113, 0xffff0000, v113
	v_pk_mul_f32 v[116:117], v[116:117], v[164:165]
	v_pk_mul_f32 v[112:113], v[118:119], v[112:113]
	v_cvt_pk_bf16_f32 v116, v116, v117
	v_cvt_pk_bf16_f32 v117, v112, v113
	v_pk_add_f32 v[118:119], v[120:121], v[160:161] op_sel_hi:[1,0]
	global_store_dwordx2 v[114:115], v[116:117], off offset:16
	s_waitcnt vmcnt(15)
	v_mov_b64_e32 v[112:113], v[212:213]
	v_lshlrev_b32_e32 v116, 16, v112
	v_and_b32_e32 v117, 0xffff0000, v112
	v_pk_mul_f32 v[116:117], v[118:119], v[116:117]
	v_lshlrev_b32_e32 v112, 16, v113
	v_and_b32_e32 v113, 0xffff0000, v113
	v_pk_add_f32 v[118:119], v[122:123], v[160:161] op_sel_hi:[1,0]
	v_cvt_pk_bf16_f32 v116, v116, v117
	v_pk_mul_f32 v[112:113], v[118:119], v[112:113]
	v_pk_add_f32 v[118:119], v[124:125], v[160:161] op_sel_hi:[1,0]
	v_cvt_pk_bf16_f32 v117, v112, v113
	s_nop 0
	global_store_dwordx2 v[114:115], v[116:117], off offset:32
	s_waitcnt vmcnt(15)
	v_mov_b64_e32 v[112:113], v[218:219]
	v_lshlrev_b32_e32 v116, 16, v112
	v_and_b32_e32 v117, 0xffff0000, v112
	v_pk_mul_f32 v[116:117], v[118:119], v[116:117]
	v_lshlrev_b32_e32 v112, 16, v113
	v_and_b32_e32 v113, 0xffff0000, v113
	v_pk_add_f32 v[118:119], v[126:127], v[160:161] op_sel_hi:[1,0]
	v_cvt_pk_bf16_f32 v116, v116, v117
	v_pk_mul_f32 v[112:113], v[118:119], v[112:113]
	s_nop 0
	v_cvt_pk_bf16_f32 v117, v112, v113
	s_nop 0
	global_store_dwordx2 v[114:115], v[116:117], off offset:48
	s_waitcnt vmcnt(15)
	v_mov_b64_e32 v[112:113], v[220:221]
	v_lshlrev_b32_e32 v116, 16, v112
	v_and_b32_e32 v117, 0xffff0000, v112
	v_lshlrev_b32_e32 v112, 16, v113
	v_and_b32_e32 v113, 0xffff0000, v113
	v_pk_mul_f32 v[96:97], v[96:97], v[116:117]
	v_pk_mul_f32 v[98:99], v[98:99], v[112:113]
	v_cvt_pk_bf16_f32 v96, v96, v97
	v_cvt_pk_bf16_f32 v97, v98, v99
	global_store_dwordx2 v[114:115], v[96:97], off offset:64
	s_waitcnt vmcnt(15)
	v_mov_b64_e32 v[96:97], v[222:223]
	v_lshlrev_b32_e32 v98, 16, v96
	v_and_b32_e32 v99, 0xffff0000, v96
	v_pk_mul_f32 v[98:99], v[100:101], v[98:99]
	v_lshlrev_b32_e32 v96, 16, v97
	v_and_b32_e32 v97, 0xffff0000, v97
	v_pk_add_f32 v[100:101], v[102:103], v[160:161] op_sel_hi:[1,0]
	v_cvt_pk_bf16_f32 v98, v98, v99
	v_pk_mul_f32 v[96:97], v[100:101], v[96:97]
	v_pk_add_f32 v[100:101], v[104:105], v[160:161] op_sel_hi:[1,0]
	v_cvt_pk_bf16_f32 v99, v96, v97
	s_nop 0
	global_store_dwordx2 v[114:115], v[98:99], off offset:80
	s_waitcnt vmcnt(15)
	v_mov_b64_e32 v[96:97], v[224:225]
	v_lshlrev_b32_e32 v98, 16, v96
	v_and_b32_e32 v99, 0xffff0000, v96
	v_pk_mul_f32 v[98:99], v[100:101], v[98:99]
	v_lshlrev_b32_e32 v96, 16, v97
	v_and_b32_e32 v97, 0xffff0000, v97
	v_pk_add_f32 v[100:101], v[106:107], v[160:161] op_sel_hi:[1,0]
	v_cvt_pk_bf16_f32 v98, v98, v99
	v_pk_mul_f32 v[96:97], v[100:101], v[96:97]
	v_pk_add_f32 v[100:101], v[108:109], v[160:161] op_sel_hi:[1,0]
	v_cvt_pk_bf16_f32 v99, v96, v97
	s_nop 0
	global_store_dwordx2 v[114:115], v[98:99], off offset:96
	s_waitcnt vmcnt(15)
	v_mov_b64_e32 v[96:97], v[226:227]
	v_lshlrev_b32_e32 v98, 16, v96
	v_and_b32_e32 v99, 0xffff0000, v96
	v_pk_mul_f32 v[98:99], v[100:101], v[98:99]
	v_lshlrev_b32_e32 v96, 16, v97
	v_and_b32_e32 v97, 0xffff0000, v97
	v_pk_add_f32 v[100:101], v[110:111], v[160:161] op_sel_hi:[1,0]
	v_cvt_pk_bf16_f32 v98, v98, v99
	v_pk_mul_f32 v[96:97], v[100:101], v[96:97]
	s_nop 0
	v_cvt_pk_bf16_f32 v99, v96, v97
	s_nop 0
	global_store_dwordx2 v[114:115], v[98:99], off offset:112
	s_waitcnt vmcnt(15)
	v_mov_b64_e32 v[96:97], v[228:229]
	v_lshlrev_b32_e32 v98, 16, v96
	v_and_b32_e32 v99, 0xffff0000, v96
	v_lshlrev_b32_e32 v96, 16, v97
	v_and_b32_e32 v97, 0xffff0000, v97
	v_pk_mul_f32 v[80:81], v[80:81], v[98:99]
	v_pk_mul_f32 v[82:83], v[82:83], v[96:97]
	v_cvt_pk_bf16_f32 v80, v80, v81
	v_cvt_pk_bf16_f32 v81, v82, v83
	global_store_dwordx2 v[114:115], v[80:81], off offset:128
	s_waitcnt vmcnt(15)
	v_mov_b64_e32 v[80:81], v[238:239]
	v_lshlrev_b32_e32 v82, 16, v80
	v_and_b32_e32 v83, 0xffff0000, v80
	v_pk_mul_f32 v[82:83], v[84:85], v[82:83]
	v_lshlrev_b32_e32 v80, 16, v81
	v_and_b32_e32 v81, 0xffff0000, v81
	v_pk_add_f32 v[84:85], v[86:87], v[160:161] op_sel_hi:[1,0]
	v_cvt_pk_bf16_f32 v82, v82, v83
	v_pk_mul_f32 v[80:81], v[84:85], v[80:81]
	v_pk_add_f32 v[84:85], v[88:89], v[160:161] op_sel_hi:[1,0]
	v_cvt_pk_bf16_f32 v83, v80, v81
	s_nop 0
	global_store_dwordx2 v[114:115], v[82:83], off offset:144
	s_waitcnt vmcnt(15)
	v_mov_b64_e32 v[80:81], v[240:241]
	v_lshlrev_b32_e32 v82, 16, v80
	v_and_b32_e32 v83, 0xffff0000, v80
	v_pk_mul_f32 v[82:83], v[84:85], v[82:83]
	v_lshlrev_b32_e32 v80, 16, v81
	v_and_b32_e32 v81, 0xffff0000, v81
	v_pk_add_f32 v[84:85], v[90:91], v[160:161] op_sel_hi:[1,0]
	v_cvt_pk_bf16_f32 v82, v82, v83
	v_pk_mul_f32 v[80:81], v[84:85], v[80:81]
	v_pk_add_f32 v[84:85], v[92:93], v[160:161] op_sel_hi:[1,0]
	v_cvt_pk_bf16_f32 v83, v80, v81
	s_nop 0
	global_store_dwordx2 v[114:115], v[82:83], off offset:160
	s_waitcnt vmcnt(15)
	v_mov_b64_e32 v[80:81], v[244:245]
	v_lshlrev_b32_e32 v82, 16, v80
	v_and_b32_e32 v83, 0xffff0000, v80
	v_pk_mul_f32 v[82:83], v[84:85], v[82:83]
	v_lshlrev_b32_e32 v80, 16, v81
	v_and_b32_e32 v81, 0xffff0000, v81
	v_pk_add_f32 v[84:85], v[94:95], v[160:161] op_sel_hi:[1,0]
	v_cvt_pk_bf16_f32 v82, v82, v83
	v_pk_mul_f32 v[80:81], v[84:85], v[80:81]
	s_nop 0
	v_cvt_pk_bf16_f32 v83, v80, v81
	s_nop 0
	global_store_dwordx2 v[114:115], v[82:83], off offset:176
	s_waitcnt vmcnt(15)
	v_mov_b64_e32 v[80:81], v[246:247]
	v_lshlrev_b32_e32 v82, 16, v80
	v_and_b32_e32 v83, 0xffff0000, v80
	v_lshlrev_b32_e32 v80, 16, v81
	v_and_b32_e32 v81, 0xffff0000, v81
	v_pk_mul_f32 v[64:65], v[64:65], v[82:83]
	v_pk_mul_f32 v[66:67], v[66:67], v[80:81]
	v_cvt_pk_bf16_f32 v64, v64, v65
	v_cvt_pk_bf16_f32 v65, v66, v67
	global_store_dwordx2 v[114:115], v[64:65], off offset:192
	s_waitcnt vmcnt(15)
	v_mov_b64_e32 v[64:65], v[248:249]
	v_lshlrev_b32_e32 v66, 16, v64
	v_and_b32_e32 v67, 0xffff0000, v64
	v_pk_mul_f32 v[66:67], v[68:69], v[66:67]
	v_lshlrev_b32_e32 v64, 16, v65
	v_and_b32_e32 v65, 0xffff0000, v65
	v_pk_add_f32 v[68:69], v[70:71], v[160:161] op_sel_hi:[1,0]
	v_cvt_pk_bf16_f32 v66, v66, v67
	v_pk_mul_f32 v[64:65], v[68:69], v[64:65]
	v_pk_add_f32 v[68:69], v[72:73], v[160:161] op_sel_hi:[1,0]
	v_cvt_pk_bf16_f32 v67, v64, v65
	s_nop 0
	global_store_dwordx2 v[114:115], v[66:67], off offset:208
	s_waitcnt vmcnt(15)
	v_mov_b64_e32 v[64:65], v[250:251]
	v_lshlrev_b32_e32 v66, 16, v64
	v_and_b32_e32 v67, 0xffff0000, v64
	v_pk_mul_f32 v[66:67], v[68:69], v[66:67]
	v_lshlrev_b32_e32 v64, 16, v65
	v_and_b32_e32 v65, 0xffff0000, v65
	v_pk_add_f32 v[68:69], v[74:75], v[160:161] op_sel_hi:[1,0]
	v_cvt_pk_bf16_f32 v66, v66, v67
	v_pk_mul_f32 v[64:65], v[68:69], v[64:65]
	v_pk_add_f32 v[68:69], v[76:77], v[160:161] op_sel_hi:[1,0]
	v_cvt_pk_bf16_f32 v67, v64, v65
	s_nop 0
	global_store_dwordx2 v[114:115], v[66:67], off offset:224
	s_waitcnt vmcnt(15)
	v_mov_b64_e32 v[64:65], v[138:139]
	v_lshlrev_b32_e32 v66, 16, v64
	v_and_b32_e32 v67, 0xffff0000, v64
	v_pk_mul_f32 v[66:67], v[68:69], v[66:67]
	v_lshlrev_b32_e32 v64, 16, v65
	v_and_b32_e32 v65, 0xffff0000, v65
	v_pk_add_f32 v[68:69], v[78:79], v[160:161] op_sel_hi:[1,0]
	v_cvt_pk_bf16_f32 v66, v66, v67
	v_pk_mul_f32 v[64:65], v[68:69], v[64:65]
	v_lshlrev_b64 v[68:69], 11, v[130:131]
	v_cvt_pk_bf16_f32 v67, v64, v65
	global_store_dwordx2 v[114:115], v[66:67], off offset:240
	v_lshlrev_b64 v[66:67], 12, v[130:131]
	v_lshl_add_u64 v[66:67], v[134:135], 0, v[66:67]
	v_lshl_add_u64 v[64:65], v[136:137], 2, s[76:77]
	v_lshl_add_u64 v[66:67], v[66:67], 0, v[128:129]
	global_load_dword v64, v[64:65], off offset:128
	v_lshl_add_u64 v[68:69], v[132:133], 0, v[68:69]
	s_branch .Lsgu_pf1
.Lsgu_pf1d:
	s_waitcnt vmcnt(16)
	v_pk_add_f32 v[48:49], v[48:49], v[64:65] op_sel_hi:[1,0]
	v_pk_add_f32 v[50:51], v[50:51], v[64:65] op_sel_hi:[1,0]
	s_waitcnt vmcnt(15)
	v_mov_b64_e32 v[70:71], v[162:163]
	v_lshlrev_b32_e32 v72, 16, v70
	v_and_b32_e32 v73, 0xffff0000, v70
	v_lshlrev_b32_e32 v70, 16, v71
	v_and_b32_e32 v71, 0xffff0000, v71
	v_pk_mul_f32 v[48:49], v[48:49], v[72:73]
	v_pk_mul_f32 v[50:51], v[50:51], v[70:71]
	v_cvt_pk_bf16_f32 v48, v48, v49
	v_cvt_pk_bf16_f32 v49, v50, v51
	v_lshl_add_u64 v[50:51], v[68:69], 0, v[128:129]
	global_store_dwordx2 v[50:51], v[48:49], off
	v_pk_add_f32 v[52:53], v[52:53], v[64:65] op_sel_hi:[1,0]
	v_pk_add_f32 v[54:55], v[54:55], v[64:65] op_sel_hi:[1,0]
	v_pk_add_f32 v[32:33], v[32:33], v[64:65] op_sel_hi:[1,0]
	v_pk_add_f32 v[34:35], v[34:35], v[64:65] op_sel_hi:[1,0]
	v_pk_add_f32 v[36:37], v[36:37], v[64:65] op_sel_hi:[1,0]
	v_pk_add_f32 v[16:17], v[16:17], v[64:65] op_sel_hi:[1,0]
	v_pk_add_f32 v[18:19], v[18:19], v[64:65] op_sel_hi:[1,0]
	v_pk_add_f32 v[20:21], v[20:21], v[64:65] op_sel_hi:[1,0]
	v_pk_add_f32 v[0:1], v[0:1], v[64:65] op_sel_hi:[1,0]
	v_pk_add_f32 v[2:3], v[2:3], v[64:65] op_sel_hi:[1,0]
	v_pk_add_f32 v[4:5], v[4:5], v[64:65] op_sel_hi:[1,0]
	s_waitcnt vmcnt(15)
	v_mov_b64_e32 v[48:49], v[210:211]
	v_lshlrev_b32_e32 v68, 16, v48
	v_and_b32_e32 v69, 0xffff0000, v48
	v_lshlrev_b32_e32 v48, 16, v49
	v_and_b32_e32 v49, 0xffff0000, v49
	v_pk_mul_f32 v[52:53], v[52:53], v[68:69]
	v_pk_mul_f32 v[48:49], v[54:55], v[48:49]
	v_cvt_pk_bf16_f32 v52, v52, v53
	v_cvt_pk_bf16_f32 v53, v48, v49
	v_pk_add_f32 v[54:55], v[56:57], v[64:65] op_sel_hi:[1,0]
	global_store_dwordx2 v[50:51], v[52:53], off offset:16
	s_waitcnt vmcnt(15)
	v_mov_b64_e32 v[48:49], v[212:213]
	v_lshlrev_b32_e32 v52, 16, v48
	v_and_b32_e32 v53, 0xffff0000, v48
	v_pk_mul_f32 v[52:53], v[54:55], v[52:53]
	v_lshlrev_b32_e32 v48, 16, v49
	v_and_b32_e32 v49, 0xffff0000, v49
	v_pk_add_f32 v[54:55], v[58:59], v[64:65] op_sel_hi:[1,0]
	v_cvt_pk_bf16_f32 v52, v52, v53
	v_pk_mul_f32 v[48:49], v[54:55], v[48:49]
	v_pk_add_f32 v[54:55], v[60:61], v[64:65] op_sel_hi:[1,0]
	v_cvt_pk_bf16_f32 v53, v48, v49
	s_nop 0
	global_store_dwordx2 v[50:51], v[52:53], off offset:32
	s_waitcnt vmcnt(15)
	v_mov_b64_e32 v[48:49], v[218:219]
	v_lshlrev_b32_e32 v52, 16, v48
	v_and_b32_e32 v53, 0xffff0000, v48
	v_pk_mul_f32 v[52:53], v[54:55], v[52:53]
	v_lshlrev_b32_e32 v48, 16, v49
	v_and_b32_e32 v49, 0xffff0000, v49
	v_pk_add_f32 v[54:55], v[62:63], v[64:65] op_sel_hi:[1,0]
	v_cvt_pk_bf16_f32 v52, v52, v53
	v_pk_mul_f32 v[48:49], v[54:55], v[48:49]
	s_nop 0
	v_cvt_pk_bf16_f32 v53, v48, v49
	s_nop 0
	global_store_dwordx2 v[50:51], v[52:53], off offset:48
	s_waitcnt vmcnt(15)
	v_mov_b64_e32 v[48:49], v[220:221]
	v_lshlrev_b32_e32 v52, 16, v48
	v_and_b32_e32 v53, 0xffff0000, v48
	v_lshlrev_b32_e32 v48, 16, v49
	v_and_b32_e32 v49, 0xffff0000, v49
	v_pk_mul_f32 v[32:33], v[32:33], v[52:53]
	v_pk_mul_f32 v[34:35], v[34:35], v[48:49]
	v_cvt_pk_bf16_f32 v32, v32, v33
	v_cvt_pk_bf16_f32 v33, v34, v35
	global_store_dwordx2 v[50:51], v[32:33], off offset:64
	s_waitcnt vmcnt(15)
	v_mov_b64_e32 v[32:33], v[222:223]
	v_lshlrev_b32_e32 v34, 16, v32
	v_and_b32_e32 v35, 0xffff0000, v32
	v_pk_mul_f32 v[34:35], v[36:37], v[34:35]
	v_lshlrev_b32_e32 v32, 16, v33
	v_and_b32_e32 v33, 0xffff0000, v33
	v_pk_add_f32 v[36:37], v[38:39], v[64:65] op_sel_hi:[1,0]
	v_cvt_pk_bf16_f32 v34, v34, v35
	v_pk_mul_f32 v[32:33], v[36:37], v[32:33]
	v_pk_add_f32 v[36:37], v[40:41], v[64:65] op_sel_hi:[1,0]
	v_cvt_pk_bf16_f32 v35, v32, v33
	s_nop 0
	global_store_dwordx2 v[50:51], v[34:35], off offset:80
	s_waitcnt vmcnt(15)
	v_mov_b64_e32 v[32:33], v[224:225]
	v_lshlrev_b32_e32 v34, 16, v32
	v_and_b32_e32 v35, 0xffff0000, v32
	v_pk_mul_f32 v[34:35], v[36:37], v[34:35]
	v_lshlrev_b32_e32 v32, 16, v33
	v_and_b32_e32 v33, 0xffff0000, v33
	v_pk_add_f32 v[36:37], v[42:43], v[64:65] op_sel_hi:[1,0]
	v_cvt_pk_bf16_f32 v34, v34, v35
	v_pk_mul_f32 v[32:33], v[36:37], v[32:33]
	v_pk_add_f32 v[36:37], v[44:45], v[64:65] op_sel_hi:[1,0]
	v_cvt_pk_bf16_f32 v35, v32, v33
	s_nop 0
	global_store_dwordx2 v[50:51], v[34:35], off offset:96
	s_waitcnt vmcnt(15)
	v_mov_b64_e32 v[32:33], v[226:227]
	v_lshlrev_b32_e32 v34, 16, v32
	v_and_b32_e32 v35, 0xffff0000, v32
	v_pk_mul_f32 v[34:35], v[36:37], v[34:35]
	v_lshlrev_b32_e32 v32, 16, v33
	v_and_b32_e32 v33, 0xffff0000, v33
	v_pk_add_f32 v[36:37], v[46:47], v[64:65] op_sel_hi:[1,0]
	v_cvt_pk_bf16_f32 v34, v34, v35
	v_pk_mul_f32 v[32:33], v[36:37], v[32:33]
	s_nop 0
	v_cvt_pk_bf16_f32 v35, v32, v33
	s_nop 0
	global_store_dwordx2 v[50:51], v[34:35], off offset:112
	s_waitcnt vmcnt(15)
	v_mov_b64_e32 v[32:33], v[228:229]
	v_lshlrev_b32_e32 v34, 16, v32
	v_and_b32_e32 v35, 0xffff0000, v32
	v_lshlrev_b32_e32 v32, 16, v33
	v_and_b32_e32 v33, 0xffff0000, v33
	v_pk_mul_f32 v[16:17], v[16:17], v[34:35]
	v_pk_mul_f32 v[18:19], v[18:19], v[32:33]
	v_cvt_pk_bf16_f32 v16, v16, v17
	v_cvt_pk_bf16_f32 v17, v18, v19
	global_store_dwordx2 v[50:51], v[16:17], off offset:128
	s_waitcnt vmcnt(15)
	v_mov_b64_e32 v[16:17], v[238:239]
	v_lshlrev_b32_e32 v18, 16, v16
	v_and_b32_e32 v19, 0xffff0000, v16
	v_pk_mul_f32 v[18:19], v[20:21], v[18:19]
	v_lshlrev_b32_e32 v16, 16, v17
	v_and_b32_e32 v17, 0xffff0000, v17
	v_pk_add_f32 v[20:21], v[22:23], v[64:65] op_sel_hi:[1,0]
	v_cvt_pk_bf16_f32 v18, v18, v19
	v_pk_mul_f32 v[16:17], v[20:21], v[16:17]
	v_pk_add_f32 v[20:21], v[24:25], v[64:65] op_sel_hi:[1,0]
	v_cvt_pk_bf16_f32 v19, v16, v17
	s_nop 0
	global_store_dwordx2 v[50:51], v[18:19], off offset:144
	s_waitcnt vmcnt(15)
	v_mov_b64_e32 v[16:17], v[240:241]
	v_lshlrev_b32_e32 v18, 16, v16
	v_and_b32_e32 v19, 0xffff0000, v16
	v_pk_mul_f32 v[18:19], v[20:21], v[18:19]
	v_lshlrev_b32_e32 v16, 16, v17
	v_and_b32_e32 v17, 0xffff0000, v17
	v_pk_add_f32 v[20:21], v[26:27], v[64:65] op_sel_hi:[1,0]
	v_cvt_pk_bf16_f32 v18, v18, v19
	v_pk_mul_f32 v[16:17], v[20:21], v[16:17]
	v_pk_add_f32 v[20:21], v[28:29], v[64:65] op_sel_hi:[1,0]
	v_cvt_pk_bf16_f32 v19, v16, v17
	s_nop 0
	global_store_dwordx2 v[50:51], v[18:19], off offset:160
	s_waitcnt vmcnt(15)
	v_mov_b64_e32 v[16:17], v[244:245]
	v_lshlrev_b32_e32 v18, 16, v16
	v_and_b32_e32 v19, 0xffff0000, v16
	v_pk_mul_f32 v[18:19], v[20:21], v[18:19]
	v_lshlrev_b32_e32 v16, 16, v17
	v_and_b32_e32 v17, 0xffff0000, v17
	v_pk_add_f32 v[20:21], v[30:31], v[64:65] op_sel_hi:[1,0]
	v_cvt_pk_bf16_f32 v18, v18, v19
	v_pk_mul_f32 v[16:17], v[20:21], v[16:17]
	s_nop 0
	v_cvt_pk_bf16_f32 v19, v16, v17
	s_nop 0
	global_store_dwordx2 v[50:51], v[18:19], off offset:176
	s_waitcnt vmcnt(15)
	v_mov_b64_e32 v[16:17], v[246:247]
	v_lshlrev_b32_e32 v18, 16, v16
	v_and_b32_e32 v19, 0xffff0000, v16
	v_lshlrev_b32_e32 v16, 16, v17
	v_and_b32_e32 v17, 0xffff0000, v17
	v_pk_mul_f32 v[0:1], v[0:1], v[18:19]
	v_pk_mul_f32 v[2:3], v[2:3], v[16:17]
	v_cvt_pk_bf16_f32 v0, v0, v1
	v_cvt_pk_bf16_f32 v1, v2, v3
	global_store_dwordx2 v[50:51], v[0:1], off offset:192
	s_waitcnt vmcnt(15)
	v_mov_b64_e32 v[0:1], v[248:249]
	v_lshlrev_b32_e32 v2, 16, v0
	v_and_b32_e32 v3, 0xffff0000, v0
	v_pk_mul_f32 v[2:3], v[4:5], v[2:3]
	v_lshlrev_b32_e32 v0, 16, v1
	v_and_b32_e32 v1, 0xffff0000, v1
	v_pk_add_f32 v[4:5], v[6:7], v[64:65] op_sel_hi:[1,0]
	v_cvt_pk_bf16_f32 v2, v2, v3
	v_pk_mul_f32 v[0:1], v[4:5], v[0:1]
	v_pk_add_f32 v[4:5], v[8:9], v[64:65] op_sel_hi:[1,0]
	v_cvt_pk_bf16_f32 v3, v0, v1
	s_nop 0
	global_store_dwordx2 v[50:51], v[2:3], off offset:208
	s_waitcnt vmcnt(15)
	v_mov_b64_e32 v[0:1], v[250:251]
	v_lshlrev_b32_e32 v2, 16, v0
	v_and_b32_e32 v3, 0xffff0000, v0
	v_pk_mul_f32 v[2:3], v[4:5], v[2:3]
	v_lshlrev_b32_e32 v0, 16, v1
	v_and_b32_e32 v1, 0xffff0000, v1
	v_pk_add_f32 v[4:5], v[10:11], v[64:65] op_sel_hi:[1,0]
	v_cvt_pk_bf16_f32 v2, v2, v3
	v_pk_mul_f32 v[0:1], v[4:5], v[0:1]
	v_pk_add_f32 v[4:5], v[12:13], v[64:65] op_sel_hi:[1,0]
	v_cvt_pk_bf16_f32 v3, v0, v1
	s_nop 0
	global_store_dwordx2 v[50:51], v[2:3], off offset:224
	s_waitcnt vmcnt(15)
	v_mov_b64_e32 v[0:1], v[138:139]
	v_lshlrev_b32_e32 v2, 16, v0
	v_and_b32_e32 v3, 0xffff0000, v0
	v_pk_mul_f32 v[2:3], v[4:5], v[2:3]
	v_lshlrev_b32_e32 v0, 16, v1
	v_and_b32_e32 v1, 0xffff0000, v1
	v_pk_add_f32 v[4:5], v[14:15], v[64:65] op_sel_hi:[1,0]
	v_cvt_pk_bf16_f32 v2, v2, v3
	v_pk_mul_f32 v[0:1], v[4:5], v[0:1]
	s_nop 0
	v_cvt_pk_bf16_f32 v3, v0, v1
	global_store_dwordx2 v[50:51], v[2:3], off offset:240
	s_andn2_b64 exec, exec, s[8:9]
	s_cbranch_execnz .LBB0_169

.Lnm_pro:
	v_lshl_add_u64 v[112:113], s[88:89], 0, v[36:37]
	v_lshl_add_u64 v[114:115], s[88:89], 0, v[58:59]
	v_add_co_u32_e32 v112, vcc, 0x8a80000, v112
	s_nop 0
	v_addc_co_u32_e32 v113, vcc, 0, v113, vcc
	global_load_dwordx4 v[0:3], v[114:115], off
	global_load_dwordx4 v[4:7], v[114:115], off offset:1024
	global_load_dwordx4 v[8:11], v[112:113], off
	global_load_dwordx4 v[12:15], v[112:113], off offset:1024
	s_branch .LBB0_318
	s_nop 0
	s_nop 0
	s_nop 0
	s_nop 0
	s_nop 0
	s_nop 0
	s_nop 0
	s_nop 0
	s_nop 0
	s_nop 0
	s_nop 0
	s_nop 0
	s_nop 0
	s_nop 0
	s_nop 0
	s_nop 0
	s_nop 0
	s_nop 0
	s_nop 0
	s_nop 0
	s_nop 0
	s_nop 0
	s_nop 0
	s_nop 0
	s_nop 0
	s_nop 0
	s_nop 0
	s_nop 0
	s_nop 0
	s_nop 0
	s_nop 0
	s_nop 0
	s_nop 0
	s_nop 0
	s_nop 0
	s_nop 0
	s_nop 0
	s_nop 0
	s_nop 0
	s_nop 0
	s_nop 0
	s_nop 0
	s_nop 0
	s_nop 0
	s_nop 0
	s_nop 0
	s_nop 0
	s_nop 0
	s_nop 0
	s_nop 0
	s_nop 0
	s_nop 0
	s_nop 0
	s_nop 0
	s_nop 0
	s_nop 0
	s_nop 0
	s_nop 0
	s_nop 0
	s_nop 0
	s_nop 0
	s_nop 0
	s_nop 0
	s_nop 0
	s_nop 0
	s_nop 0
	s_nop 0
	s_nop 0
	s_nop 0
	s_nop 0
	s_nop 0
	s_nop 0
	s_nop 0
	s_nop 0
	s_nop 0
	s_nop 0
	s_nop 0
	s_nop 0
	s_nop 0
	s_nop 0
	s_nop 0
	s_nop 0
	s_nop 0
	s_nop 0
	s_nop 0
	s_nop 0
	s_nop 0
	s_nop 0
	s_nop 0
	s_nop 0
	s_nop 0
	s_nop 0
	s_nop 0
	s_nop 0
	s_nop 0
	s_nop 0
	s_nop 0
	s_nop 0
	s_nop 0
	s_nop 0
	s_nop 0
	s_nop 0
	s_nop 0
	s_nop 0
	s_nop 0
	s_nop 0
	s_nop 0
	s_nop 0
	s_nop 0
	s_nop 0
	s_nop 0
	s_nop 0
	s_nop 0
	s_nop 0
	s_nop 0
	s_nop 0
	s_nop 0
	s_nop 0
	s_nop 0
	s_nop 0
	s_nop 0
	s_nop 0
	s_nop 0
	s_nop 0
	s_nop 0
	s_nop 0
	s_nop 0
	s_nop 0
	s_nop 0
	s_nop 0
	s_nop 0
	s_nop 0
	s_nop 0
	s_nop 0
	s_nop 0
	s_nop 0
	s_nop 0
	s_nop 0
	s_nop 0
	s_nop 0
	s_nop 0
	s_nop 0
	s_nop 0
	s_nop 0
	s_nop 0
	s_nop 0
	s_nop 0
	s_nop 0
	s_nop 0
	s_nop 0
	s_nop 0
	s_nop 0
	s_nop 0
	s_nop 0
	s_nop 0
	s_nop 0
	s_nop 0
	s_nop 0
	s_nop 0
	s_nop 0
	s_nop 0
	s_nop 0
	s_nop 0
	s_nop 0
	s_nop 0
	s_nop 0
	s_nop 0
	s_nop 0
	s_nop 0
	s_nop 0
	s_nop 0
	s_nop 0
	s_nop 0
	s_nop 0
	s_nop 0
	s_nop 0
	s_nop 0
	s_nop 0
	s_nop 0
	s_nop 0
	s_nop 0
	s_nop 0
	s_nop 0
	s_nop 0
	s_nop 0
	s_nop 0
	s_nop 0
	s_nop 0
	s_nop 0
	s_nop 0
	s_nop 0
	s_nop 0
	s_nop 0
	s_nop 0
	s_nop 0
	s_nop 0
	s_nop 0
	s_nop 0
	s_nop 0
	s_nop 0
	s_nop 0
	s_nop 0
	s_nop 0
	s_nop 0
	s_nop 0
	s_nop 0
	s_nop 0
	s_nop 0
	s_nop 0
	s_nop 0
	s_nop 0
	s_nop 0
	s_nop 0
	s_nop 0
	s_nop 0
	s_nop 0
	s_nop 0
	s_nop 0
	s_nop 0
	s_nop 0
	s_nop 0
	s_nop 0
	s_nop 0
	s_nop 0
	s_nop 0
	s_nop 0
	s_nop 0
	s_nop 0
	s_nop 0
	s_nop 0
	s_nop 0
	s_nop 0
	s_nop 0
	s_nop 0
	s_nop 0
	s_nop 0
	s_nop 0
	s_nop 0
	s_nop 0
	s_nop 0
	s_nop 0
	s_nop 0
	s_nop 0
	s_nop 0
	s_nop 0
	s_nop 0
	s_nop 0
	s_nop 0
	s_nop 0
	s_nop 0
	s_nop 0
	s_nop 0
	s_nop 0
	s_nop 0
	s_nop 0
	s_nop 0
	s_nop 0
	s_nop 0
	s_nop 0
	s_nop 0
	s_nop 0
	s_nop 0
	s_nop 0
	s_nop 0
	s_nop 0
	s_nop 0
	s_nop 0
	s_nop 0
	s_nop 0
	s_nop 0
	s_nop 0
	s_nop 0
	s_nop 0
	s_nop 0
	s_nop 0
	s_nop 0
	s_nop 0
	s_nop 0
	s_nop 0
	s_nop 0
	s_nop 0
	s_nop 0
	s_nop 0
	s_nop 0
	s_nop 0
	s_nop 0
	s_nop 0
	s_nop 0
	s_nop 0
	s_nop 0
	s_nop 0
	s_nop 0
	s_nop 0
	s_nop 0
	s_nop 0
	s_nop 0
	s_nop 0
	s_nop 0
	s_nop 0
	s_nop 0
	s_nop 0
	s_nop 0
	s_nop 0
	s_nop 0
	s_nop 0
	s_nop 0
	s_nop 0
	s_nop 0
	s_nop 0
	s_nop 0
	s_nop 0
	s_nop 0
	s_nop 0
	s_nop 0
	s_nop 0
	s_nop 0
	s_nop 0
	s_nop 0
	s_nop 0
	s_nop 0
	s_nop 0
	s_nop 0
	s_nop 0
	s_nop 0
	s_nop 0
	s_nop 0
	s_nop 0
	s_nop 0
	s_nop 0
	s_nop 0
	s_nop 0
	s_nop 0
	s_nop 0
	s_nop 0
	s_nop 0
	s_nop 0
	s_nop 0
	s_nop 0
	s_nop 0
	s_nop 0
	s_nop 0
	s_nop 0
	s_nop 0
	s_nop 0
	s_nop 0
	s_nop 0
	s_nop 0
	s_nop 0
	s_nop 0
	s_nop 0
	s_nop 0
	s_nop 0
	s_nop 0
	s_nop 0
	s_nop 0
	s_nop 0
	s_nop 0
	s_nop 0
	s_nop 0
	s_nop 0
	s_nop 0
	s_nop 0
	s_nop 0
	s_nop 0
	s_nop 0
	s_nop 0
	s_nop 0
	s_nop 0
	s_nop 0
	s_nop 0
	s_nop 0
	s_nop 0
	s_nop 0
	s_nop 0
.Lfbp_addr:
	v_alignbit_b32 v212, v191, v190, 2
	v_add_u32_e32 v214, v201, v212
	v_ashrrev_i32_e32 v215, 31, v214
	v_lshlrev_b64 v[236:237], 11, v[214:215]
	v_lshl_add_u64 v[236:237], s[6:7], 0, v[236:237]
	v_lshl_add_u64 v[236:237], v[236:237], 0, v[128:129]
	v_add_u32_e32 v214, v202, v212
	v_ashrrev_i32_e32 v215, 31, v214
	v_lshlrev_b64 v[238:239], 11, v[214:215]
	v_lshl_add_u64 v[238:239], s[6:7], 0, v[238:239]
	v_lshl_add_u64 v[238:239], v[238:239], 0, v[128:129]
	v_mbcnt_lo_u32_b32 v220, -1, 0
	v_mbcnt_hi_u32_b32 v220, -1, v220
	v_and_b32_e32 v220, 32, v220
	v_lshrrev_b32_e32 v220, 2, v220
	v_mov_b32_e32 v221, 0
	v_lshl_add_u64 v[236:237], v[236:237], 0, v[220:221]
	v_lshl_add_u64 v[238:239], v[238:239], 0, v[220:221]
	s_branch .Lfbp_addrd

.Lsgu_pf0:
	global_load_dwordx2 v[162:163], v[166:167], off
	global_load_dwordx2 v[210:211], v[166:167], off offset:16
	global_load_dwordx2 v[212:213], v[166:167], off offset:32
	global_load_dwordx2 v[218:219], v[166:167], off offset:48
	global_load_dwordx2 v[220:221], v[166:167], off offset:64
	global_load_dwordx2 v[222:223], v[166:167], off offset:80
	global_load_dwordx2 v[224:225], v[166:167], off offset:96
	global_load_dwordx2 v[226:227], v[166:167], off offset:112
	global_load_dwordx2 v[228:229], v[166:167], off offset:128
	global_load_dwordx2 v[238:239], v[166:167], off offset:144
	global_load_dwordx2 v[240:241], v[166:167], off offset:160
	global_load_dwordx2 v[244:245], v[166:167], off offset:176
	global_load_dwordx2 v[246:247], v[166:167], off offset:192
	global_load_dwordx2 v[248:249], v[166:167], off offset:208
	global_load_dwordx2 v[250:251], v[166:167], off offset:224
	global_load_dwordx2 v[138:139], v[166:167], off offset:240
	s_branch .Lsgu_pf0d
.Lsgu_pf1:
	global_load_dwordx2 v[162:163], v[66:67], off
	global_load_dwordx2 v[210:211], v[66:67], off offset:16
	global_load_dwordx2 v[212:213], v[66:67], off offset:32
	global_load_dwordx2 v[218:219], v[66:67], off offset:48
	global_load_dwordx2 v[220:221], v[66:67], off offset:64
	global_load_dwordx2 v[222:223], v[66:67], off offset:80
	global_load_dwordx2 v[224:225], v[66:67], off offset:96
	global_load_dwordx2 v[226:227], v[66:67], off offset:112
	global_load_dwordx2 v[228:229], v[66:67], off offset:128
	global_load_dwordx2 v[238:239], v[66:67], off offset:144
	global_load_dwordx2 v[240:241], v[66:67], off offset:160
	global_load_dwordx2 v[244:245], v[66:67], off offset:176
	global_load_dwordx2 v[246:247], v[66:67], off offset:192
	global_load_dwordx2 v[248:249], v[66:67], off offset:208
	global_load_dwordx2 v[250:251], v[66:67], off offset:224
	global_load_dwordx2 v[138:139], v[66:67], off offset:240
	s_branch .Lsgu_pf1d
